# gate/up phase: XCD groups (xcc_id&3) start 2us apart so their epilogue store bursts do not coincide
# baseline (speedup 1.0000x reference)
; #define PG8_BAR __builtin_amdgcn_s_barrier()
; #define LAS __attribute__((address_space(3)))
; template <class Epi, class Sched, bool ALIGN_EPI = false, bool SP2 = false>
; __device__ __forceinline__ void gemm_phase(PG8_LAS unsigned char* lds, const Gemm g, const Sched& S, const Epi& E) {
;     int tid_l = pg8_tid(lds); asm volatile("" : "+v"(tid_l));
;     const int tid = tid_l, wid = __builtin_amdgcn_readfirstlane(tid >> 6), lane = tid & 63, wr = wid >> 2, wc = wid & 3, fr = lane & 15, fq = lane >> 4;
;     const int K = g.K, nt = K / BK;
;     unsigned voffA[2], voffB[2];
; #pragma unroll
;     for (int i = 0; i < 2; ++i) { int R, C; stage_rc(tid * 16 + i * 8192, R, C); const int Rb = Epi::PERM ? ((R & ~31) + perm32(R & 31)) : R;
;         voffA[i] = (unsigned)(R * K + C) * 2u; voffB[i] = (unsigned)(Rb * K + C) * 2u; }
;     const size_t kstep = (size_t)(BK * 2);
;     const size_t hstep = (size_t)HALF * K * 2;
;     const size_t tstep = 2 * hstep;
;     const unsigned ldsw = (unsigned)wid * 1024u;
;     const int aoff = lds_byte(wr * 64 + fr, fq * 8), boff = lds_byte(wc * 32 + fr, fq * 8);
;     ...
;     Unit cur, nxt; int ui = 0;
;     if (!S.next(0, cur)) return;
;     f32x4 acc[2][2][4][2];
; #pragma unroll
;     for (int a = 0; a < 2; ++a)
; #pragma unroll
;         for (int b = 0; b < 2; ++b)
; #pragma unroll
;             for (int m = 0; m < 4; ++m)
; #pragma unroll
;                 for (int n = 0; n < 2; ++n) acc[a][b][m][n] = (f32x4){0.f, 0.f, 0.f, 0.f};
;     bf16x8 At[4][2], B0[2][2], B1[2][2];
;     const char* cA = (const char*)g.A + (size_t)cur.pm * tstep; const char* cB = (const char*)g.Bt + (size_t)cur.pn * tstep;
;     S.a_ready(cur);
;     if constexpr (SP2) {
;         PG8_STAGE(PG8_SB(0, 0), cB, voffB); PG8_STAGE(PG8_SB(0, 1), cB + hstep, voffB); PG8_STAGE(PG8_SA(0, 0), cA, voffA); PG8_STAGE(PG8_SA(0, 1), cA + hstep, voffA);
;         if (wr == 1) PG8_BAR;
; __global__ void __launch_bounds__(512, 2) fwd_megakernel(Params p) {
;     ...
;         {
;             LWS(ws);
;             pg8::Gemm g{(const bf16_t*)(ws + WS_XB), (const bf16_t*)(ws + WS_WGU) + (size_t)l * NGU * DM, MP, NGU, DM}; pg8::StaticOrder S; S.init(MP, NGU, G, bx);
;             EpiSwiGLU E{(bf16_t*)(ws + WS_HID), (const float*)(ws + WS_SSQB), (LAS float*)(lds + LDS_RC), 2 + 2 * l};
;             pg8::gemm_phase<EpiSwiGLU, pg8::StaticOrder, true, true>(lds, g, S, E);
.LBB0_1755:
	s_or_b64 exec, exec, s[8:9]
	s_mov_b64 s[8:9], 0
	s_waitcnt lgkmcnt(0)
	s_barrier
	s_getreg_b32 s100, hwreg(HW_REG_XCC_ID, 0, 4)
	s_and_b32 s100, s100, 3
	s_mul_i32 s100, s100, 200
	s_memrealtime s[0:1]
	s_waitcnt lgkmcnt(0)
	s_add_u32 s100, s100, s0
.Lstagger_gu:
	s_memrealtime s[0:1]
	s_waitcnt lgkmcnt(0)
	s_sub_u32 s1, s100, s0
	s_cmp_gt_i32 s1, 0
	s_cbranch_scc1 .Lstagger_gu
	s_getreg_b32 s0, hwreg(HW_REG_HW_ID, 0, 6)
	s_and_b32 s0, s0, 63
	s_lshl_b32 s0, s0, 2
	s_add_i32 s0, s0, 0
	s_add_i32 s0, s0, 0x20100
	v_mov_b32_e32 v1, s0
	ds_read_b32 v1, v1
	s_waitcnt lgkmcnt(0)
	v_readfirstlane_b32 s0, v1
	s_nop 1
	v_lshl_add_u32 v11, s0, 6, v190
	v_readlane_b32 s0, v254, 45
	v_readlane_b32 s1, v254, 46
	s_andn2_b64 vcc, exec, s[0:1]
	v_readfirstlane_b32 s18, v11
	s_cbranch_vccnz .LBB0_1821
	v_lshlrev_b32_e32 v1, 4, v11
	v_add_u32_e32 v2, 0x2000, v1
	v_ashrrev_i32_e32 v3, 31, v2
	v_lshrrev_b32_e32 v3, 22, v3
	v_add_u32_e32 v3, v2, v3
	v_ashrrev_i32_e32 v10, 10, v3
	v_mul_i32_i24_e32 v3, 0x400, v10
	v_sub_u32_e32 v2, v2, v3
	v_lshrrev_b32_e32 v3, 4, v2
	s_add_u32 s10, s58, s8
	v_bitop3_b32 v2, v3, v2, 32 bitop3:0x6c
	s_addc_u32 s11, s59, s9
	v_ashrrev_i32_e32 v3, 31, v2
	s_add_u32 s0, s10, 0x4000000
	v_lshrrev_b32_e32 v3, 26, v3
	s_addc_u32 s1, s11, 0
	v_add_u32_e32 v3, v2, v3
	v_lshlrev_b32_e32 v4, 3, v10
	s_add_u32 s4, s10, s79
	v_ashrrev_i32_e32 v12, 6, v3
	v_and_b32_e32 v4, -16, v4
	s_addc_u32 s5, s11, 0
	v_add_u32_e32 v4, v12, v4
	s_add_u32 s34, s4, 0xc00000
	v_and_b32_e32 v5, 3, v12
	s_mov_b32 s4, 0x1fffe0
	v_lshrrev_b32_e32 v6, 2, v4
	v_lshlrev_b32_e32 v7, 1, v4
	v_and_b32_e32 v3, 0xc0, v3
	v_and_or_b32 v5, v4, s4, v5
	v_and_b32_e32 v6, 4, v6
	v_and_b32_e32 v7, 24, v7
	v_sub_u32_e32 v2, v2, v3
	v_or3_b32 v5, v5, v6, v7
	v_lshlrev_b32_e32 v6, 5, v10
	v_ashrrev_i16_sdwa v2, v197, sext(v2) dst_sel:DWORD dst_unused:UNUSED_PAD src0_sel:DWORD src1_sel:BYTE_0
	v_and_b32_e32 v6, 32, v6
	v_bfe_i32 v13, v2, 0, 16
	v_add_lshl_u32 v2, v6, v13, 1
	v_lshl_add_u32 v150, v5, 11, v2
	v_lshl_add_u32 v152, v4, 11, v2
	v_bfe_i32 v2, v11, 27, 1
	v_lshrrev_b32_e32 v2, 22, v2
	v_add_u32_e32 v2, v1, v2
	v_and_b32_e32 v2, 0xfffffc00, v2
	v_sub_u32_e32 v1, v1, v2
	v_lshrrev_b32_e32 v2, 4, v1
	v_ashrrev_i32_e32 v3, 31, v11
	v_bitop3_b32 v1, v2, v1, 32 bitop3:0x6c
	v_lshrrev_b32_e32 v3, 26, v3
	v_ashrrev_i32_e32 v2, 31, v1
	v_add_u32_e32 v3, v11, v3
	v_lshrrev_b32_e32 v2, 26, v2
	v_ashrrev_i32_e32 v15, 6, v3
	v_add_u32_e32 v2, v1, v2
	v_lshlrev_b32_e32 v3, 3, v15
	v_ashrrev_i32_e32 v14, 6, v2
	v_and_b32_e32 v3, -16, v3
	v_add_u32_e32 v3, v14, v3
	v_and_b32_e32 v4, 3, v14
	v_lshrrev_b32_e32 v5, 2, v3
	v_lshlrev_b32_e32 v6, 1, v3
	v_and_b32_e32 v2, 0xc0, v2
	s_addc_u32 s35, s5, 0
	s_ashr_i32 s9, s18, 6
	v_and_or_b32 v4, v3, s4, v4
	v_and_b32_e32 v5, 4, v5
	v_and_b32_e32 v6, 24, v6
	v_sub_u32_e32 v1, v1, v2
	s_ashr_i32 s8, s18, 8
	s_lshl_b32 s36, s9, 10
	v_or3_b32 v4, v4, v5, v6
	v_lshlrev_b32_e32 v5, 5, v15
	v_ashrrev_i16_sdwa v1, v197, sext(v1) dst_sel:DWORD dst_unused:UNUSED_PAD src0_sel:DWORD src1_sel:BYTE_0
	v_readlane_b32 s4, v255, 2
	v_and_b32_e32 v5, 32, v5
	v_bfe_i32 v16, v1, 0, 16
	v_readlane_b32 s5, v255, 3
	s_add_u32 s28, s34, s4
	v_add_lshl_u32 v1, v5, v16, 1
	s_addc_u32 s29, s35, s5
	s_add_i32 s37, s36, 0
	v_lshl_add_u32 v154, v4, 11, v1
	s_add_i32 m0, s37, 0x10000
	v_lshl_add_u32 v156, v3, 11, v1
	global_load_lds_dwordx4 v154, s[28:29]
	s_add_i32 m0, s37, 0x12000
	s_add_u32 s4, s28, 0x40000
	global_load_lds_dwordx4 v150, s[28:29]
	s_addc_u32 s5, s29, 0
	s_add_i32 m0, s37, 0x14000
	v_mov_b32_e32 v155, v0
	global_load_lds_dwordx4 v154, s[4:5]
	s_add_i32 m0, s37, 0x16000
	v_mov_b32_e32 v151, v0
	global_load_lds_dwordx4 v150, s[4:5]
	v_readlane_b32 s4, v255, 0
	v_readlane_b32 s5, v255, 1
	s_add_u32 s12, s0, s4
	s_addc_u32 s13, s1, s5
	s_add_i32 s38, s37, 0x2000
	s_mov_b32 m0, s37
	s_add_u32 s4, s12, 0x40000
	global_load_lds_dwordx4 v156, s[12:13]
	s_mov_b32 m0, s38
	s_addc_u32 s5, s13, 0
	s_add_i32 s39, s37, 0x4000
	global_load_lds_dwordx4 v152, s[12:13]
	s_mov_b32 m0, s39
	s_add_i32 s40, s37, 0x6000
	global_load_lds_dwordx4 v156, s[4:5]
	s_mov_b32 m0, s40
	v_mov_b32_e32 v157, v0
	global_load_lds_dwordx4 v152, s[4:5]
	v_mov_b32_e32 v153, v0
	s_cmp_eq_u32 s8, 1
	v_lshl_add_u64 v[8:9], s[28:29], 0, v[154:155]
	v_lshl_add_u64 v[6:7], s[28:29], 0, v[150:151]
	v_lshl_add_u64 v[2:3], s[12:13], 0, v[156:157]
	s_cselect_b64 s[14:15], -1, 0
	s_cmp_lg_u32 s8, 1
	v_lshl_add_u64 v[4:5], s[12:13], 0, v[152:153]
	s_cbranch_scc1 .LBB0_1758
	s_barrier

; __global__ void __launch_bounds__(512, 2) fwd_megakernel(Params p) {
	.amdhsa_kernel _Z14fwd_megakernel6Params
		.amdhsa_group_segment_fixed_size 0
		.amdhsa_private_segment_fixed_size 0
		.amdhsa_kernarg_size 448
		.amdhsa_user_sgpr_count 2
		.amdhsa_user_sgpr_dispatch_ptr 0
		.amdhsa_user_sgpr_queue_ptr 0
		.amdhsa_user_sgpr_kernarg_segment_ptr 1
		.amdhsa_user_sgpr_dispatch_id 0
		.amdhsa_user_sgpr_kernarg_preload_length 0
		.amdhsa_user_sgpr_kernarg_preload_offset 0
		.amdhsa_user_sgpr_private_segment_size 0
		.amdhsa_uses_dynamic_stack 0
		.amdhsa_enable_private_segment 0
		.amdhsa_system_sgpr_workgroup_id_x 1
		.amdhsa_system_sgpr_workgroup_id_y 0
		.amdhsa_system_sgpr_workgroup_id_z 0
		.amdhsa_system_sgpr_workgroup_info 0
		.amdhsa_system_vgpr_workitem_id 2
		.amdhsa_next_free_vgpr 256
		.amdhsa_next_free_sgpr 102
		.amdhsa_accum_offset 256
		.amdhsa_reserve_vcc 1
		.amdhsa_float_round_mode_32 0
		.amdhsa_float_round_mode_16_64 0
		.amdhsa_float_denorm_mode_32 3
		.amdhsa_float_denorm_mode_16_64 3
		.amdhsa_dx10_clamp 1
		.amdhsa_ieee_mode 1
		.amdhsa_fp16_overflow 0
		.amdhsa_tg_split 0
		.amdhsa_exception_fp_ieee_invalid_op 0
		.amdhsa_exception_fp_denorm_src 0
		.amdhsa_exception_fp_ieee_div_zero 0
		.amdhsa_exception_fp_ieee_overflow 0
		.amdhsa_exception_fp_ieee_underflow 0
		.amdhsa_exception_fp_ieee_inexact 0
		.amdhsa_exception_int_div_zero 0
	.end_amdhsa_kernel

; __global__ void __launch_bounds__(512, 2) fwd_megakernel(Params p) {
amdhsa.kernels:
  - .agpr_count:     0
    .args:
      - .offset:         0
        .size:           192
        .value_kind:     by_value
      - .offset:         192
        .size:           4
        .value_kind:     hidden_block_count_x
      - .offset:         196
        .size:           4
        .value_kind:     hidden_block_count_y
      - .offset:         200
        .size:           4
        .value_kind:     hidden_block_count_z
      - .offset:         204
        .size:           2
        .value_kind:     hidden_group_size_x
      - .offset:         206
        .size:           2
        .value_kind:     hidden_group_size_y
      - .offset:         208
        .size:           2
        .value_kind:     hidden_group_size_z
      - .offset:         210
        .size:           2
        .value_kind:     hidden_remainder_x
      - .offset:         212
        .size:           2
        .value_kind:     hidden_remainder_y
      - .offset:         214
        .size:           2
        .value_kind:     hidden_remainder_z
      - .offset:         232
        .size:           8
        .value_kind:     hidden_global_offset_x
      - .offset:         240
        .size:           8
        .value_kind:     hidden_global_offset_y
      - .offset:         248
        .size:           8
        .value_kind:     hidden_global_offset_z
      - .offset:         256
        .size:           2
        .value_kind:     hidden_grid_dims
      - .offset:         280
        .size:           8
        .value_kind:     hidden_multigrid_sync_arg
      - .offset:         312
        .size:           4
        .value_kind:     hidden_dynamic_lds_size
    .group_segment_fixed_size: 0
    .kernarg_segment_align: 8
    .kernarg_segment_size: 448
    .language:       OpenCL C
    .language_version:
      - 2
      - 0
    .max_flat_workgroup_size: 512
    .name:           _Z14fwd_megakernel6Params
    .private_segment_fixed_size: 0
    .sgpr_count:     108
    .sgpr_spill_count: 108
    .symbol:         _Z14fwd_megakernel6Params.kd
    .uniform_work_group_size: 1
    .uses_dynamic_stack: false
    .vgpr_count:     256
    .vgpr_spill_count: 0
    .wavefront_size: 64
